# merged GEMM + MLA attention: per-tile LDS-DMA block renamed to free VGPRs and sunk below first 4 QK MFMAs
# speedup vs baseline: 1.0011x; 1.0011x over previous
.LBB0_543:
	s_mov_b32 s23, s17
	s_mov_b32 s17, s0
	s_add_i32 s71, 0, 0x10000
	v_add_u32_e32 v203, s71, v173
	ds_read_b128 v[66:69], v203
	ds_read_b128 v[70:73], v203 offset:8192
	v_add_u32_e32 v204, s71, v175
	ds_read_b128 v[206:209], v204
	ds_read_b128 v[210:213], v204 offset:8192
	v_add_u32_e32 v205, s71, v177
	s_waitcnt lgkmcnt(0)
	v_mfma_f32_32x32x16_bf16 v[82:97], v[66:69], v[142:145], 0
	s_add_i32 s0, 0, 0x16000
	v_exp_f32_e32 v240, v146
	v_add_f32_e32 v146, 0, v229
	v_add_f32_e32 v146, v231, v146
	v_add_f32_e32 v146, v227, v146
	v_add_f32_e32 v146, v230, v146
	v_add_f32_e32 v146, v226, v146
	v_mfma_f32_32x32x16_bf16 v[66:81], v[70:73], v[142:145], 0
	v_add_f32_e32 v146, v228, v146
	v_add_f32_e32 v146, v224, v146
	v_add_f32_e32 v146, v225, v146
	v_add_f32_e32 v146, v221, v146
	v_add_f32_e32 v146, v223, v146
	v_add_f32_e32 v146, v220, v146
	v_add_f32_e32 v146, v222, v146
	v_mfma_f32_32x32x16_bf16 v[82:97], v[206:209], v[138:141], v[82:97]
	v_exp_f32_e32 v164, v164
	v_add_f32_e32 v146, v217, v146
	v_exp_f32_e32 v165, v165
	v_add_f32_e32 v146, v219, v146
	v_exp_f32_e32 v197, v162
	v_add_f32_e32 v146, v216, v146
	v_add_f32_e32 v146, v218, v146
	v_mfma_f32_32x32x16_bf16 v[66:81], v[210:213], v[138:141], v[66:81]
	ds_read_b128 v[206:209], v205
	ds_read_b128 v[210:213], v205 offset:8192
	v_mov_b32_e32 v245, v172
	s_add_u32 s4, s38, s20
	v_ashrrev_i32_e32 v250, 4, v245
	v_xor_b32_e32 v246, v250, v245
	v_lshlrev_b32_e32 v246, 3, v246
	v_lshrrev_b32_e32 v247, 1, v245
	v_and_b32_e32 v246, 0x78, v246
	v_and_b32_e32 v255, 8, v247
	v_lshrrev_b32_e32 v247, 1, v250
	v_bfe_u32 v254, v245, 2, 2
	v_and_b32_e32 v248, 4, v247
	v_lshl_or_b32 v246, v250, 11, v246
	v_and_or_b32 v250, v250, s75, v255
	v_lshlrev_b32_e32 v247, 3, v245
	v_or3_b32 v250, v250, v248, v254
	v_and_b32_e32 v251, 0x60, v245
	v_and_b32_e32 v249, 24, v247
	v_lshlrev_b32_e32 v250, 11, v250
	v_or3_b32 v250, v250, v251, v249
	v_ashrrev_i32_e32 v247, 31, v246
	s_addc_u32 s5, s39, s21
	v_ashrrev_i32_e32 v251, 31, v250
	v_lshl_add_u64 v[246:247], v[246:247], 1, s[4:5]
	s_mov_b64 s[24:25], 0x149ec400
	v_lshl_add_u64 v[250:251], v[250:251], 1, s[4:5]
	s_mov_b64 s[4:5], 0x149ec500
	s_mov_b32 m0, s90
	v_lshl_add_u64 v[248:249], v[246:247], 0, s[24:25]
	v_lshl_add_u64 v[254:255], v[250:251], 0, s[4:5]
	s_mov_b64 s[4:5], 0x14a0c400
	s_lshl_b32 s18, s22, 14
	global_load_lds_dwordx4 v[248:249], off
	v_lshl_add_u64 v[246:247], v[246:247], 0, s[4:5]
	s_mov_b32 m0, s91
	s_add_i32 s1, s89, s18
	global_load_lds_dwordx4 v[246:247], off
	s_mov_b32 m0, s1
	s_mov_b64 s[4:5], 0x14a0c500
	global_load_lds_dwordx4 v[254:255], off
	v_lshl_add_u64 v[246:247], v[250:251], 0, s[4:5]
	s_add_i32 m0, s1, 0x2000
	s_add_u32 s4, s38, s88
	global_load_lds_dwordx4 v[246:247], off
	v_lshrrev_b32_e32 v247, 4, v245
	v_lshrrev_b32_e32 v246, 3, v245
	v_xor_b32_e32 v247, v247, v245
	v_mul_lo_u32 v246, v246, s76
	v_lshlrev_b32_e32 v247, 3, v247
	v_and_or_b32 v246, v247, 56, v246
	v_ashrrev_i32_e32 v247, 31, v246
	s_addc_u32 s5, s39, s87
	v_lshl_add_u64 v[246:247], v[246:247], 1, s[4:5]
	v_lshl_add_u64 v[246:247], v[246:247], 0, s[36:37]
	s_mov_b32 m0, s92
	s_nop 0
	global_load_lds_dwordx4 v[246:247], off
	v_exp_f32_e32 v156, v156
	v_add_f32_e32 v146, v164, v146
	v_exp_f32_e32 v157, v157
	v_add_f32_e32 v146, v165, v146
	v_add_f32_e32 v146, v197, v146
	v_exp_f32_e32 v241, v147
	s_waitcnt lgkmcnt(0)
	v_mfma_f32_32x32x16_bf16 v[82:97], v[206:209], v[134:137], v[82:97]
	v_add_u32_e32 v206, s71, v179
	v_add_u32_e32 v207, s71, v181
	v_mfma_f32_32x32x16_bf16 v[66:81], v[210:213], v[134:137], v[66:81]
	ds_read_b128 v[208:211], v206
	ds_read_b128 v[212:215], v206 offset:8192
	s_waitcnt lgkmcnt(0)
	v_mfma_f32_32x32x16_bf16 v[82:97], v[208:211], v[130:133], v[82:97]
	v_mfma_f32_32x32x16_bf16 v[66:81], v[212:215], v[130:133], v[66:81]
	ds_read_b128 v[208:211], v207
	ds_read_b128 v[212:215], v207 offset:8192
	s_waitcnt lgkmcnt(0)
	v_mfma_f32_32x32x16_bf16 v[82:97], v[208:211], v[126:129], v[82:97]
	v_add_u32_e32 v208, s71, v183
	v_add_u32_e32 v209, s71, v187
	v_mfma_f32_32x32x16_bf16 v[66:81], v[212:215], v[126:129], v[66:81]
	ds_read_b128 v[210:213], v208
	ds_read_b128 v[232:235], v208 offset:8192
	s_waitcnt lgkmcnt(0)
	v_mfma_f32_32x32x16_bf16 v[82:97], v[210:213], v[122:125], v[82:97]
	v_mfma_f32_32x32x16_bf16 v[66:81], v[232:235], v[122:125], v[66:81]
	ds_read_b128 v[210:213], v209
	ds_read_b128 v[232:235], v209 offset:8192
	s_waitcnt lgkmcnt(0)
	v_mfma_f32_32x32x16_bf16 v[82:97], v[210:213], v[118:121], v[82:97]
	v_add_u32_e32 v210, s71, v189
	v_add_u32_e32 v211, s0, v191
	v_mfma_f32_32x32x16_bf16 v[66:81], v[232:235], v[118:121], v[66:81]
	ds_read_b128 v[212:215], v210
	ds_read_b128 v[232:235], v210 offset:8192
	s_waitcnt lgkmcnt(0)
	v_mfma_f32_32x32x16_bf16 v[82:97], v[212:215], v[114:117], v[82:97]
	v_mfma_f32_32x32x16_bf16 v[66:81], v[232:235], v[114:117], v[66:81]
	ds_read_b128 v[212:215], v211
	ds_read_b128 v[232:235], v211 offset:4096
	s_waitcnt lgkmcnt(0)
	v_mfma_f32_32x32x16_bf16 v[82:97], v[212:215], v[110:113], v[82:97]
	v_add_u32_e32 v212, s0, v193
	v_add_u32_e32 v213, s0, v195
	v_add_u32_e32 v214, s0, v198
	v_exp_f32_e32 v215, v163
	s_nop 0
	v_add_f32_e32 v146, v215, v146
	v_mfma_f32_32x32x16_bf16 v[66:81], v[232:235], v[110:113], v[66:81]
	ds_read_b128 v[232:235], v212
	ds_read_b128 v[236:239], v212 offset:4096
	v_add_f32_e32 v146, v156, v146
	v_add_f32_e32 v146, v157, v146
	s_waitcnt lgkmcnt(0)
	v_mfma_f32_32x32x16_bf16 v[82:97], v[232:235], v[106:109], v[82:97]
	v_mfma_f32_32x32x16_bf16 v[66:81], v[236:239], v[106:109], v[66:81]
	ds_read_b128 v[232:235], v213
	ds_read_b128 v[236:239], v213 offset:4096
	s_waitcnt lgkmcnt(0)
	v_mfma_f32_32x32x16_bf16 v[82:97], v[232:235], v[102:105], v[82:97]
	v_mfma_f32_32x32x16_bf16 v[66:81], v[236:239], v[102:105], v[66:81]
	ds_read_b128 v[232:235], v214
	ds_read_b128 v[236:239], v214 offset:4096
	s_waitcnt lgkmcnt(0)
	v_mfma_f32_32x32x16_bf16 v[82:97], v[232:235], v[98:101], v[82:97]
	v_exp_f32_e32 v232, v154
	v_exp_f32_e32 v233, v155
	v_exp_f32_e32 v234, v152
	v_exp_f32_e32 v235, v153
	v_add_f32_e32 v146, v232, v146
	v_add_f32_e32 v146, v233, v146
	v_add_f32_e32 v146, v234, v146
	v_mfma_f32_32x32x16_bf16 v[66:81], v[236:239], v[98:101], v[66:81]
	v_exp_f32_e32 v236, v150
	v_exp_f32_e32 v237, v151
	v_exp_f32_e32 v238, v148
	v_exp_f32_e32 v239, v149
	v_add_f32_e32 v146, v235, v146
	v_add_f32_e32 v146, v236, v146
	v_add_f32_e32 v146, v237, v146
	v_add_f32_e32 v146, v238, v146
	v_add_f32_e32 v146, v239, v146
	v_add_f32_e32 v146, v240, v146
	v_add_f32_e32 v162, v241, v146
	v_mov_b32_e32 v163, v162
	s_nop 1
	v_permlane32_swap_b32_e32 v162, v163
	v_cvt_pk_bf16_f32 v146, v229, v231
	v_cvt_pk_bf16_f32 v147, v227, v230
	v_cvt_pk_bf16_f32 v148, v226, v228
	v_cvt_pk_bf16_f32 v149, v224, v225
	v_cvt_pk_bf16_f32 v150, v221, v223
	v_cvt_pk_bf16_f32 v151, v220, v222
	v_cvt_pk_bf16_f32 v152, v217, v219
	v_cvt_pk_bf16_f32 v153, v216, v218
	v_cvt_pk_bf16_f32 v154, v164, v165
	v_cvt_pk_bf16_f32 v155, v197, v215
	v_cvt_pk_bf16_f32 v156, v156, v157
	v_cvt_pk_bf16_f32 v157, v232, v233
	v_cvt_pk_bf16_f32 v216, v234, v235
	v_cvt_pk_bf16_f32 v217, v236, v237
	v_cvt_pk_bf16_f32 v218, v238, v239
	v_cvt_pk_bf16_f32 v219, v240, v241
	s_nop 0
	v_permlane32_swap_b32_e32 v146, v148
	v_permlane32_swap_b32_e32 v147, v149
	v_permlane32_swap_b32_e32 v150, v152
	v_permlane32_swap_b32_e32 v151, v153
	v_permlane32_swap_b32_e32 v154, v156
	v_permlane32_swap_b32_e32 v155, v157
	v_permlane32_swap_b32_e32 v216, v218
	v_permlane32_swap_b32_e32 v217, v219
	s_lshl_b32 s24, s17, 14
	v_add_u32_e32 v197, s24, v200
	ds_read_b64_tr_b16 v[220:221], v197 offset:0
	ds_read_b64_tr_b16 v[222:223], v197 offset:0x800
	ds_read_b64_tr_b16 v[224:225], v197 offset:0x1000
	ds_read_b64_tr_b16 v[226:227], v197 offset:0x1800
	ds_read_b64_tr_b16 v[228:229], v197 offset:0x2000
	ds_read_b64_tr_b16 v[230:231], v197 offset:0x2800
	ds_read_b64_tr_b16 v[232:233], v197 offset:0x3000
	ds_read_b64_tr_b16 v[234:235], v197 offset:0x3800
	s_waitcnt lgkmcnt(0)
	s_nop 0
	v_mfma_f32_32x32x16_bf16 v[2:17], v[146:149], v[220:223], v[2:17]
	ds_read_b64_tr_b16 v[220:221], v197 offset:0x200
	ds_read_b64_tr_b16 v[222:223], v197 offset:0xa00
	v_max_f32_e32 v164, v83, v83
	v_max_f32_e32 v165, v82, v82
	v_max_f32_e32 v164, v165, v164
	v_max3_f32 v164, v164, v84, v85
	v_max3_f32 v164, v164, v86, v87
	v_mfma_f32_32x32x16_bf16 v[2:17], v[150:153], v[224:227], v[2:17]
	ds_read_b64_tr_b16 v[224:225], v197 offset:0x1200
	ds_read_b64_tr_b16 v[226:227], v197 offset:0x1a00
	v_max3_f32 v164, v164, v88, v89
	v_max3_f32 v164, v164, v90, v91
	v_max3_f32 v164, v164, v92, v93
	v_max3_f32 v164, v164, v94, v95
	v_max3_f32 v164, v164, v96, v97
	v_mfma_f32_32x32x16_bf16 v[2:17], v[154:157], v[228:231], v[2:17]
	ds_read_b64_tr_b16 v[228:229], v197 offset:0x2200
	ds_read_b64_tr_b16 v[230:231], v197 offset:0x2a00
	ds_read_b64_tr_b16 v[236:237], v197 offset:0x3200
	ds_read_b64_tr_b16 v[238:239], v197 offset:0x3a00
	s_waitcnt lgkmcnt(0)
	v_mfma_f32_32x32x16_bf16 v[2:17], v[216:219], v[232:235], v[2:17]
	v_mfma_f32_32x32x16_bf16 v[50:65], v[146:149], v[220:223], v[50:65]
	v_max3_f32 v164, v164, v66, v67
	v_max3_f32 v164, v164, v68, v69
	v_max3_f32 v164, v164, v70, v71
	v_max3_f32 v164, v164, v72, v73
	v_max3_f32 v164, v164, v74, v75
	v_max3_f32 v164, v164, v76, v77
	v_max3_f32 v164, v164, v78, v79
	v_mfma_f32_32x32x16_bf16 v[50:65], v[150:153], v[224:227], v[50:65]
	v_max3_f32 v164, v164, v80, v81
	v_mov_b32_e32 v165, v164
	s_nop 1
	v_permlane32_swap_b32_e32 v164, v165
	ds_read_b64_tr_b16 v[220:221], v197 offset:0x400
	v_max_f32_e32 v165, v165, v165
	v_max_f32_e32 v164, v164, v164
	v_mfma_f32_32x32x16_bf16 v[50:65], v[154:157], v[228:231], v[50:65]
	ds_read_b64_tr_b16 v[222:223], v197 offset:0xc00
	v_max_f32_e32 v164, v164, v165
	v_max_f32_e32 v165, v202, v202
	ds_read_b64_tr_b16 v[224:225], v197 offset:0x1400
	v_max_f32_e32 v165, v165, v164
	ds_read_b64_tr_b16 v[226:227], v197 offset:0x1c00
	v_sub_f32_e32 v215, v164, v202
	v_mfma_f32_32x32x16_bf16 v[50:65], v[216:219], v[236:239], v[50:65]
	v_sub_f32_e32 v164, v202, v165
	ds_read_b64_tr_b16 v[228:229], v197 offset:0x2400
	v_mul_f32_e32 v164, 0x3dd53b94, v164
	ds_read_b64_tr_b16 v[230:231], v197 offset:0x2c00
	v_exp_f32_e32 v164, v164
	ds_read_b64_tr_b16 v[232:233], v197 offset:0x3400
	v_cmp_ge_f32_e32 vcc, s77, v215
	ds_read_b64_tr_b16 v[234:235], v197 offset:0x3c00
	s_cmp_eq_u64 vcc, exec
	s_waitcnt lgkmcnt(0)
	s_cselect_b64 s[4:5], -1, 0
	v_cndmask_b32_e64 v164, v164, 1.0, s[4:5]
	v_mfma_f32_32x32x16_bf16 v[34:49], v[146:149], v[220:223], v[34:49]
	ds_read_b64_tr_b16 v[220:221], v197 offset:0x600
	ds_read_b64_tr_b16 v[222:223], v197 offset:0xe00
	v_mfma_f32_32x32x16_bf16 v[34:49], v[150:153], v[224:227], v[34:49]
	ds_read_b64_tr_b16 v[224:225], v197 offset:0x1600
	ds_read_b64_tr_b16 v[226:227], v197 offset:0x1e00
	v_mfma_f32_32x32x16_bf16 v[34:49], v[154:157], v[228:231], v[34:49]
	ds_read_b64_tr_b16 v[228:229], v197 offset:0x2600
	ds_read_b64_tr_b16 v[230:231], v197 offset:0x2e00
	ds_read_b64_tr_b16 v[236:237], v197 offset:0x3600
	ds_read_b64_tr_b16 v[238:239], v197 offset:0x3e00
	s_waitcnt lgkmcnt(0)
	v_mfma_f32_32x32x16_bf16 v[34:49], v[216:219], v[232:235], v[34:49]
	v_mfma_f32_32x32x16_bf16 v[18:33], v[146:149], v[220:223], v[18:33]
	v_cmp_gt_f32_e32 vcc, 1.0, v164
	v_mfma_f32_32x32x16_bf16 v[18:33], v[150:153], v[224:227], v[18:33]
	v_mfma_f32_32x32x16_bf16 v[18:33], v[154:157], v[228:231], v[18:33]
	v_mfma_f32_32x32x16_bf16 v[18:33], v[216:219], v[236:239], v[18:33]
	s_cbranch_vccz .LBB0_547
	s_and_saveexec_b64 s[0:1], s[2:3]
	ds_write_b32 v170, v164 offset:128
	s_or_b64 exec, exec, s[0:1]
	s_waitcnt lgkmcnt(0)
	ds_read_b128 v[146:149], v158 offset:224
	ds_read_b128 v[150:153], v158 offset:192
	ds_read_b128 v[154:157], v158 offset:160
	ds_read_b128 v[216:219], v158 offset:128
	s_waitcnt lgkmcnt(0)
	v_pk_mul_f32 v[16:17], v[16:17], v[148:149]
	v_pk_mul_f32 v[12:13], v[12:13], v[152:153]
	v_pk_mul_f32 v[8:9], v[8:9], v[156:157]
	v_pk_mul_f32 v[4:5], v[4:5], v[218:219]
	v_pk_mul_f32 v[14:15], v[14:15], v[146:147]
	v_pk_mul_f32 v[10:11], v[10:11], v[150:151]
	v_pk_mul_f32 v[6:7], v[6:7], v[154:155]
	v_pk_mul_f32 v[2:3], v[2:3], v[216:217]
	v_pk_mul_f32 v[64:65], v[64:65], v[148:149]
	v_pk_mul_f32 v[60:61], v[60:61], v[152:153]
	v_pk_mul_f32 v[56:57], v[56:57], v[156:157]
	v_pk_mul_f32 v[52:53], v[52:53], v[218:219]
	v_pk_mul_f32 v[62:63], v[62:63], v[146:147]
	v_pk_mul_f32 v[58:59], v[58:59], v[150:151]
	v_pk_mul_f32 v[54:55], v[54:55], v[154:155]
	v_pk_mul_f32 v[50:51], v[50:51], v[216:217]
	v_pk_mul_f32 v[48:49], v[48:49], v[148:149]
	v_pk_mul_f32 v[44:45], v[44:45], v[152:153]
	v_pk_mul_f32 v[40:41], v[40:41], v[156:157]
	v_pk_mul_f32 v[36:37], v[36:37], v[218:219]
	v_pk_mul_f32 v[46:47], v[46:47], v[146:147]
	v_pk_mul_f32 v[42:43], v[42:43], v[150:151]
	v_pk_mul_f32 v[38:39], v[38:39], v[154:155]
	v_pk_mul_f32 v[34:35], v[34:35], v[216:217]
	v_pk_mul_f32 v[32:33], v[32:33], v[148:149]
	v_pk_mul_f32 v[28:29], v[28:29], v[152:153]
	v_pk_mul_f32 v[24:25], v[24:25], v[156:157]
	v_pk_mul_f32 v[20:21], v[20:21], v[218:219]
	v_pk_mul_f32 v[30:31], v[30:31], v[146:147]
	v_pk_mul_f32 v[26:27], v[26:27], v[150:151]
	v_pk_mul_f32 v[22:23], v[22:23], v[154:155]
	v_pk_mul_f32 v[18:19], v[18:19], v[216:217]
.LBB0_547:
	s_waitcnt vmcnt(0)
	s_add_i32 s0, s19, 1
	s_cmp_ge_u32 s0, s86
	s_cselect_b32 s98, 1, 0
	s_waitcnt vmcnt(0)
	s_barrier
.LBB0_549:
	v_cndmask_b32_e64 v165, v165, v202, s[4:5]
	v_mul_f32_e32 v154, 0xbdd53b94, v165
	v_fmamk_f32 v82, v82, 0x3dd53b94, v154
	v_fmamk_f32 v83, v83, 0x3dd53b94, v154
	v_fmamk_f32 v84, v84, 0x3dd53b94, v154
	v_fmamk_f32 v85, v85, 0x3dd53b94, v154
	v_fmamk_f32 v86, v86, 0x3dd53b94, v154
	v_fmamk_f32 v87, v87, 0x3dd53b94, v154
	v_fmamk_f32 v88, v88, 0x3dd53b94, v154
	v_fmamk_f32 v89, v89, 0x3dd53b94, v154
	v_fmamk_f32 v90, v90, 0x3dd53b94, v154
	v_fmamk_f32 v91, v91, 0x3dd53b94, v154
	v_fmamk_f32 v92, v92, 0x3dd53b94, v154
	v_fmamk_f32 v93, v93, 0x3dd53b94, v154
	v_fmamk_f32 v94, v94, 0x3dd53b94, v154
	v_fmamk_f32 v95, v95, 0x3dd53b94, v154
	v_fmamk_f32 v96, v96, 0x3dd53b94, v154
	v_fmamk_f32 v97, v97, 0x3dd53b94, v154
	v_fmamk_f32 v202, v69, 0x3dd53b94, v154
	v_fmamk_f32 v215, v70, 0x3dd53b94, v154
	v_fmamk_f32 v232, v79, 0x3dd53b94, v154
	v_fmamk_f32 v233, v80, 0x3dd53b94, v154
	v_fmamk_f32 v155, v66, 0x3dd53b94, v154
	v_fmamk_f32 v156, v67, 0x3dd53b94, v154
	v_fmamk_f32 v157, v68, 0x3dd53b94, v154
	v_fmamk_f32 v216, v71, 0x3dd53b94, v154
	v_fmamk_f32 v217, v72, 0x3dd53b94, v154
	v_fmamk_f32 v218, v73, 0x3dd53b94, v154
	v_fmamk_f32 v219, v74, 0x3dd53b94, v154
	v_fmamk_f32 v220, v75, 0x3dd53b94, v154
	v_fmamk_f32 v221, v76, 0x3dd53b94, v154
	v_fmamk_f32 v222, v77, 0x3dd53b94, v154
	v_fmamk_f32 v223, v78, 0x3dd53b94, v154
	v_exp_f32_e32 v224, v82
	v_exp_f32_e32 v225, v83
	v_exp_f32_e32 v226, v84
	v_exp_f32_e32 v227, v85
	v_exp_f32_e32 v228, v86
	v_exp_f32_e32 v229, v87
	v_exp_f32_e32 v230, v88
	v_exp_f32_e32 v231, v89
	v_exp_f32_e32 v234, v90
	v_exp_f32_e32 v235, v91
	v_exp_f32_e32 v236, v92
	v_exp_f32_e32 v237, v93
	v_exp_f32_e32 v238, v94
	v_exp_f32_e32 v239, v95
	v_exp_f32_e32 v240, v96
	v_exp_f32_e32 v241, v97
	v_fmac_f32_e32 v154, 0x3dd53b94, v81
	ds_read_b128 v[66:69], v174 offset:49152
	ds_read_b128 v[70:73], v174 offset:57344
	ds_read_b128 v[146:149], v176 offset:49152
	ds_read_b128 v[150:153], v176 offset:57344
	v_exp_f32_e32 v155, v155
	v_exp_f32_e32 v156, v156
	s_waitcnt lgkmcnt(0)
	v_mfma_f32_32x32x16_bf16 v[82:97], v[66:69], v[142:145], 0
	v_exp_f32_e32 v157, v157
	v_exp_f32_e32 v202, v202
	v_exp_f32_e32 v215, v215
	v_exp_f32_e32 v216, v216
	v_exp_f32_e32 v217, v217
	v_exp_f32_e32 v218, v218
	v_exp_f32_e32 v219, v219
	v_mfma_f32_32x32x16_bf16 v[66:81], v[70:73], v[142:145], 0
	v_exp_f32_e32 v220, v220
	v_exp_f32_e32 v221, v221
	v_exp_f32_e32 v222, v222
	v_exp_f32_e32 v223, v223
	v_exp_f32_e32 v242, v232
	v_exp_f32_e32 v243, v233
	v_exp_f32_e32 v244, v154
	v_mfma_f32_32x32x16_bf16 v[82:97], v[146:149], v[138:141], v[82:97]
	v_mfma_f32_32x32x16_bf16 v[66:81], v[150:153], v[138:141], v[66:81]
	ds_read_b128 v[146:149], v178 offset:49152
	ds_read_b128 v[150:153], v178 offset:57344
	s_cmp_lg_u32 s98, 0
	s_cbranch_scc1 .Lattn_mla_nopf
	v_mov_b32_e32 v245, v172
	s_add_u32 s0, s38, s20
	v_ashrrev_i32_e32 v250, 4, v245
	v_xor_b32_e32 v246, v250, v245
	v_lshlrev_b32_e32 v246, 3, v246
	v_lshrrev_b32_e32 v247, 1, v245
	v_and_b32_e32 v246, 0x78, v246
	v_and_b32_e32 v255, 8, v247
	v_lshrrev_b32_e32 v247, 1, v250
	v_bfe_u32 v254, v245, 2, 2
	v_and_b32_e32 v248, 4, v247
	v_lshl_or_b32 v246, v250, 11, v246
	v_and_or_b32 v250, v250, s75, v255
	v_lshlrev_b32_e32 v247, 3, v245
	v_or3_b32 v250, v250, v248, v254
	v_and_b32_e32 v251, 0x60, v245
	v_and_b32_e32 v249, 24, v247
	v_ashrrev_i32_e32 v247, 31, v246
	s_addc_u32 s1, s39, s21
	v_lshlrev_b32_e32 v250, 11, v250
	v_lshl_add_u64 v[246:247], v[246:247], 1, s[0:1]
	v_or3_b32 v250, v250, v251, v249
	s_mov_b32 m0, s93
	v_lshl_add_u64 v[248:249], v[246:247], 0, s[42:43]
	v_ashrrev_i32_e32 v251, 31, v250
	v_lshl_add_u64 v[250:251], v[250:251], 1, s[0:1]
	global_load_lds_dwordx4 v[248:249], off
	v_lshl_add_u64 v[246:247], v[246:247], 0, s[46:47]
	s_mov_b32 m0, s94
	s_add_i32 s0, s89, s24
	v_lshl_add_u64 v[254:255], v[250:251], 0, s[44:45]
	global_load_lds_dwordx4 v[246:247], off
	s_mov_b32 m0, s0
	v_lshl_add_u64 v[246:247], v[250:251], 0, s[50:51]
	global_load_lds_dwordx4 v[254:255], off
	s_add_i32 m0, s0, 0x2000
	s_add_u32 s0, s38, s88
	global_load_lds_dwordx4 v[246:247], off
	v_lshrrev_b32_e32 v247, 4, v245
	v_lshrrev_b32_e32 v246, 3, v245
	v_xor_b32_e32 v247, v247, v245
	v_mul_lo_u32 v246, v246, s76
	v_lshlrev_b32_e32 v247, 3, v247
	v_and_or_b32 v246, v247, 56, v246
	v_ashrrev_i32_e32 v247, 31, v246
	s_addc_u32 s1, s39, s87
	v_lshl_add_u64 v[246:247], v[246:247], 1, s[0:1]
	v_lshl_add_u64 v[246:247], v[246:247], 0, s[58:59]
	s_mov_b32 m0, s95
	s_nop 0
	global_load_lds_dwordx4 v[246:247], off
.Lattn_mla_nopf:
	s_waitcnt lgkmcnt(0)
	v_mfma_f32_32x32x16_bf16 v[82:97], v[146:149], v[134:137], v[82:97]
	v_mfma_f32_32x32x16_bf16 v[66:81], v[150:153], v[134:137], v[66:81]
	ds_read_b128 v[146:149], v180 offset:49152
	ds_read_b128 v[150:153], v180 offset:57344
	s_waitcnt lgkmcnt(0)
	v_mfma_f32_32x32x16_bf16 v[82:97], v[146:149], v[130:133], v[82:97]
	v_mfma_f32_32x32x16_bf16 v[66:81], v[150:153], v[130:133], v[66:81]
	ds_read_b128 v[146:149], v182 offset:49152
	ds_read_b128 v[150:153], v182 offset:57344
	s_waitcnt lgkmcnt(0)
	v_mfma_f32_32x32x16_bf16 v[82:97], v[146:149], v[126:129], v[82:97]
	v_mfma_f32_32x32x16_bf16 v[66:81], v[150:153], v[126:129], v[66:81]
	ds_read_b128 v[146:149], v186 offset:49152
	ds_read_b128 v[150:153], v186 offset:57344
	s_waitcnt lgkmcnt(0)
	v_mfma_f32_32x32x16_bf16 v[82:97], v[146:149], v[122:125], v[82:97]
	v_mfma_f32_32x32x16_bf16 v[66:81], v[150:153], v[122:125], v[66:81]
	ds_read_b128 v[146:149], v188 offset:49152
	ds_read_b128 v[150:153], v188 offset:57344
	s_waitcnt lgkmcnt(0)
	v_mfma_f32_32x32x16_bf16 v[82:97], v[146:149], v[118:121], v[82:97]
	v_mfma_f32_32x32x16_bf16 v[66:81], v[150:153], v[118:121], v[66:81]
	ds_read_b128 v[146:149], v190 offset:49152
	ds_read_b128 v[150:153], v190 offset:57344
	s_waitcnt lgkmcnt(0)
	v_mfma_f32_32x32x16_bf16 v[82:97], v[146:149], v[114:117], v[82:97]
	v_mfma_f32_32x32x16_bf16 v[66:81], v[150:153], v[114:117], v[66:81]
	ds_read_b128 v[146:149], v192
	ds_read_b128 v[150:153], v192 offset:4096
	s_waitcnt lgkmcnt(0)
	v_mfma_f32_32x32x16_bf16 v[82:97], v[146:149], v[110:113], v[82:97]
	v_mfma_f32_32x32x16_bf16 v[66:81], v[150:153], v[110:113], v[66:81]
	ds_read_b128 v[146:149], v194
	ds_read_b128 v[150:153], v194 offset:4096
	s_waitcnt lgkmcnt(0)
	v_mfma_f32_32x32x16_bf16 v[82:97], v[146:149], v[106:109], v[82:97]
	v_mfma_f32_32x32x16_bf16 v[66:81], v[150:153], v[106:109], v[66:81]
	ds_read_b128 v[146:149], v196
	ds_read_b128 v[150:153], v196 offset:4096
	s_waitcnt lgkmcnt(0)
	v_mfma_f32_32x32x16_bf16 v[82:97], v[146:149], v[102:105], v[82:97]
	v_mfma_f32_32x32x16_bf16 v[66:81], v[150:153], v[102:105], v[66:81]
	ds_read_b128 v[146:149], v199
	ds_read_b128 v[150:153], v199 offset:4096
	s_waitcnt lgkmcnt(0)
	v_mfma_f32_32x32x16_bf16 v[82:97], v[146:149], v[98:101], v[82:97]
	v_add_f32_e32 v146, 0, v224
	v_add_f32_e32 v146, v225, v146
	v_add_f32_e32 v146, v226, v146
	v_add_f32_e32 v146, v227, v146
	v_add_f32_e32 v146, v228, v146
	v_add_f32_e32 v146, v229, v146
	v_add_f32_e32 v146, v230, v146
	v_add_f32_e32 v146, v231, v146
	v_add_f32_e32 v146, v234, v146
	v_add_f32_e32 v146, v235, v146
	v_add_f32_e32 v146, v236, v146
	v_add_f32_e32 v146, v237, v146
	v_add_f32_e32 v146, v238, v146
	v_add_f32_e32 v146, v239, v146
	v_add_f32_e32 v146, v240, v146
	v_add_f32_e32 v146, v241, v146
	v_add_f32_e32 v146, v155, v146
	v_add_f32_e32 v146, v156, v146
	v_add_f32_e32 v146, v157, v146
	v_add_f32_e32 v146, v202, v146
	v_add_f32_e32 v146, v215, v146
	v_add_f32_e32 v146, v216, v146
	v_add_f32_e32 v146, v217, v146
	v_add_f32_e32 v146, v218, v146
	v_add_f32_e32 v146, v219, v146
	v_add_f32_e32 v146, v220, v146
	v_mfma_f32_32x32x16_bf16 v[66:81], v[150:153], v[98:101], v[66:81]
	v_add_f32_e32 v146, v221, v146
	v_add_f32_e32 v146, v222, v146
	v_add_f32_e32 v146, v223, v146
	v_add_f32_e32 v146, v242, v146
	v_add_f32_e32 v146, v243, v146
	v_add_f32_e32 v232, v244, v146
	v_mov_b32_e32 v233, v232
	s_nop 1
	v_permlane32_swap_b32_e32 v232, v233
	v_cvt_pk_bf16_f32 v146, v224, v225
	v_cvt_pk_bf16_f32 v147, v226, v227
	v_cvt_pk_bf16_f32 v148, v228, v229
	v_cvt_pk_bf16_f32 v149, v230, v231
	v_cvt_pk_bf16_f32 v150, v234, v235
	v_cvt_pk_bf16_f32 v151, v236, v237
	v_cvt_pk_bf16_f32 v152, v238, v239
	v_cvt_pk_bf16_f32 v153, v240, v241
	v_cvt_pk_bf16_f32 v154, v155, v156
	v_cvt_pk_bf16_f32 v155, v157, v202
	v_cvt_pk_bf16_f32 v156, v215, v216
	v_cvt_pk_bf16_f32 v157, v217, v218
	v_cvt_pk_bf16_f32 v216, v219, v220
	v_cvt_pk_bf16_f32 v217, v221, v222
	v_cvt_pk_bf16_f32 v218, v223, v242
	v_cvt_pk_bf16_f32 v219, v243, v244
	s_nop 0
	v_permlane32_swap_b32_e32 v146, v148
	v_permlane32_swap_b32_e32 v147, v149
	v_permlane32_swap_b32_e32 v150, v152
	v_permlane32_swap_b32_e32 v151, v153
	v_permlane32_swap_b32_e32 v154, v156
	v_permlane32_swap_b32_e32 v155, v157
	v_permlane32_swap_b32_e32 v216, v218
	v_permlane32_swap_b32_e32 v217, v219
	v_lshl_add_u32 v242, s23, 14, v200
	ds_read_b64_tr_b16 v[220:221], v242 offset:0
	ds_read_b64_tr_b16 v[222:223], v242 offset:0x800
	ds_read_b64_tr_b16 v[224:225], v242 offset:0x1000
	ds_read_b64_tr_b16 v[226:227], v242 offset:0x1800
	ds_read_b64_tr_b16 v[228:229], v242 offset:0x2000
	ds_read_b64_tr_b16 v[230:231], v242 offset:0x2800
	ds_read_b64_tr_b16 v[234:235], v242 offset:0x3000
	ds_read_b64_tr_b16 v[236:237], v242 offset:0x3800
	s_waitcnt lgkmcnt(0)
	s_nop 0
	v_mfma_f32_32x32x16_bf16 v[2:17], v[146:149], v[220:223], v[2:17]
	ds_read_b64_tr_b16 v[220:221], v242 offset:0x200
	ds_read_b64_tr_b16 v[222:223], v242 offset:0xa00
	v_max_f32_e32 v202, v83, v83
	v_max_f32_e32 v215, v82, v82
	v_max_f32_e32 v202, v215, v202
	v_max3_f32 v202, v202, v84, v85
	v_max3_f32 v202, v202, v86, v87
	v_mfma_f32_32x32x16_bf16 v[2:17], v[150:153], v[224:227], v[2:17]
	ds_read_b64_tr_b16 v[224:225], v242 offset:0x1200
	ds_read_b64_tr_b16 v[226:227], v242 offset:0x1a00
	v_max3_f32 v202, v202, v88, v89
	v_max3_f32 v202, v202, v90, v91
	v_max3_f32 v202, v202, v92, v93
	v_max3_f32 v202, v202, v94, v95
	v_max3_f32 v202, v202, v96, v97
	v_mfma_f32_32x32x16_bf16 v[2:17], v[154:157], v[228:231], v[2:17]
	ds_read_b64_tr_b16 v[228:229], v242 offset:0x2200
	ds_read_b64_tr_b16 v[230:231], v242 offset:0x2a00
	ds_read_b64_tr_b16 v[238:239], v242 offset:0x3200
	ds_read_b64_tr_b16 v[240:241], v242 offset:0x3a00
	s_waitcnt lgkmcnt(0)
	v_mfma_f32_32x32x16_bf16 v[2:17], v[216:219], v[234:237], v[2:17]
	v_mfma_f32_32x32x16_bf16 v[50:65], v[146:149], v[220:223], v[50:65]
	v_max3_f32 v202, v202, v66, v67
	v_max3_f32 v202, v202, v68, v69
	v_max3_f32 v202, v202, v70, v71
	v_max3_f32 v202, v202, v72, v73
	v_max3_f32 v202, v202, v74, v75
	v_max3_f32 v202, v202, v76, v77
	v_max3_f32 v202, v202, v78, v79
	v_mfma_f32_32x32x16_bf16 v[50:65], v[150:153], v[224:227], v[50:65]
	v_max3_f32 v202, v202, v80, v81
	v_mov_b32_e32 v215, v202
	s_nop 1
	v_permlane32_swap_b32_e32 v202, v215
	v_max_f32_e32 v215, v215, v215
	v_max_f32_e32 v202, v202, v202
	v_max_f32_e32 v202, v202, v215
	v_max_f32_e32 v220, v165, v165
	v_sub_f32_e32 v215, v202, v165
	v_max_f32_e32 v202, v220, v202
	v_sub_f32_e32 v220, v165, v202
	v_mul_f32_e32 v220, 0x3dd53b94, v220
	v_mfma_f32_32x32x16_bf16 v[50:65], v[154:157], v[228:231], v[50:65]
	v_exp_f32_e32 v220, v220
	v_cmp_ge_f32_e32 vcc, s77, v215
	s_cmp_eq_u64 vcc, exec
	s_cselect_b64 s[4:5], -1, 0
	v_cndmask_b32_e64 v215, v220, 1.0, s[4:5]
	ds_read_b64_tr_b16 v[220:221], v242 offset:0x400
	ds_read_b64_tr_b16 v[222:223], v242 offset:0xc00
	ds_read_b64_tr_b16 v[224:225], v242 offset:0x1400
	v_mfma_f32_32x32x16_bf16 v[50:65], v[216:219], v[238:241], v[50:65]
	ds_read_b64_tr_b16 v[226:227], v242 offset:0x1c00
	ds_read_b64_tr_b16 v[228:229], v242 offset:0x2400
	ds_read_b64_tr_b16 v[230:231], v242 offset:0x2c00
	ds_read_b64_tr_b16 v[234:235], v242 offset:0x3400
	ds_read_b64_tr_b16 v[236:237], v242 offset:0x3c00
	s_waitcnt lgkmcnt(0)
	v_mfma_f32_32x32x16_bf16 v[34:49], v[146:149], v[220:223], v[34:49]
	ds_read_b64_tr_b16 v[220:221], v242 offset:0x600
	ds_read_b64_tr_b16 v[222:223], v242 offset:0xe00
	v_mfma_f32_32x32x16_bf16 v[34:49], v[150:153], v[224:227], v[34:49]
	ds_read_b64_tr_b16 v[224:225], v242 offset:0x1600
	ds_read_b64_tr_b16 v[226:227], v242 offset:0x1e00
	v_mfma_f32_32x32x16_bf16 v[34:49], v[154:157], v[228:231], v[34:49]
	ds_read_b64_tr_b16 v[228:229], v242 offset:0x2600
	ds_read_b64_tr_b16 v[230:231], v242 offset:0x2e00
	ds_read_b64_tr_b16 v[238:239], v242 offset:0x3600
	ds_read_b64_tr_b16 v[240:241], v242 offset:0x3e00
	s_waitcnt lgkmcnt(0)
	v_mfma_f32_32x32x16_bf16 v[34:49], v[216:219], v[234:237], v[34:49]
	v_mfma_f32_32x32x16_bf16 v[18:33], v[146:149], v[220:223], v[18:33]
	v_cmp_gt_f32_e32 vcc, 1.0, v215
	v_mfma_f32_32x32x16_bf16 v[18:33], v[150:153], v[224:227], v[18:33]
	v_mfma_f32_32x32x16_bf16 v[18:33], v[154:157], v[228:231], v[18:33]
	v_mfma_f32_32x32x16_bf16 v[18:33], v[216:219], v[238:241], v[18:33]
	s_cbranch_vccz .LBB0_553
	s_and_saveexec_b64 s[0:1], s[2:3]
	ds_write_b32 v170, v215 offset:128
	s_or_b64 exec, exec, s[0:1]
	s_waitcnt lgkmcnt(0)
	ds_read_b128 v[146:149], v158 offset:224
	ds_read_b128 v[150:153], v158 offset:192
	ds_read_b128 v[154:157], v158 offset:160
	ds_read_b128 v[216:219], v158 offset:128
	s_waitcnt lgkmcnt(0)
	v_pk_mul_f32 v[16:17], v[16:17], v[148:149]
	v_pk_mul_f32 v[12:13], v[12:13], v[152:153]
	v_pk_mul_f32 v[8:9], v[8:9], v[156:157]
	v_pk_mul_f32 v[4:5], v[4:5], v[218:219]
	v_pk_mul_f32 v[14:15], v[14:15], v[146:147]
	v_pk_mul_f32 v[10:11], v[10:11], v[150:151]
	v_pk_mul_f32 v[6:7], v[6:7], v[154:155]
	v_pk_mul_f32 v[2:3], v[2:3], v[216:217]
	v_pk_mul_f32 v[64:65], v[64:65], v[148:149]
	v_pk_mul_f32 v[60:61], v[60:61], v[152:153]
	v_pk_mul_f32 v[56:57], v[56:57], v[156:157]
	v_pk_mul_f32 v[52:53], v[52:53], v[218:219]
	v_pk_mul_f32 v[62:63], v[62:63], v[146:147]
	v_pk_mul_f32 v[58:59], v[58:59], v[150:151]
	v_pk_mul_f32 v[54:55], v[54:55], v[154:155]
	v_pk_mul_f32 v[50:51], v[50:51], v[216:217]
	v_pk_mul_f32 v[48:49], v[48:49], v[148:149]
	v_pk_mul_f32 v[44:45], v[44:45], v[152:153]
	v_pk_mul_f32 v[40:41], v[40:41], v[156:157]
	v_pk_mul_f32 v[36:37], v[36:37], v[218:219]
	v_pk_mul_f32 v[46:47], v[46:47], v[146:147]
	v_pk_mul_f32 v[42:43], v[42:43], v[150:151]
	v_pk_mul_f32 v[38:39], v[38:39], v[154:155]
	v_pk_mul_f32 v[34:35], v[34:35], v[216:217]
	v_pk_mul_f32 v[32:33], v[32:33], v[148:149]
	v_pk_mul_f32 v[28:29], v[28:29], v[152:153]
	v_pk_mul_f32 v[24:25], v[24:25], v[156:157]
	v_pk_mul_f32 v[20:21], v[20:21], v[218:219]
	v_pk_mul_f32 v[30:31], v[30:31], v[146:147]
	v_pk_mul_f32 v[26:27], v[26:27], v[150:151]
	v_pk_mul_f32 v[22:23], v[22:23], v[154:155]
	v_pk_mul_f32 v[18:19], v[18:19], v[216:217]

	.amdhsa_kernel _Z8fwd_mega6Params
		.amdhsa_group_segment_fixed_size 0
		.amdhsa_private_segment_fixed_size 0
		.amdhsa_kernarg_size 424
		.amdhsa_user_sgpr_count 2
		.amdhsa_user_sgpr_dispatch_ptr 0
		.amdhsa_user_sgpr_queue_ptr 0
		.amdhsa_user_sgpr_kernarg_segment_ptr 1
		.amdhsa_user_sgpr_dispatch_id 0
		.amdhsa_user_sgpr_kernarg_preload_length 0
		.amdhsa_user_sgpr_kernarg_preload_offset 0
		.amdhsa_user_sgpr_private_segment_size 0
		.amdhsa_uses_dynamic_stack 0
		.amdhsa_enable_private_segment 0
		.amdhsa_system_sgpr_workgroup_id_x 1
		.amdhsa_system_sgpr_workgroup_id_y 0
		.amdhsa_system_sgpr_workgroup_id_z 0
		.amdhsa_system_sgpr_workgroup_info 0
		.amdhsa_system_vgpr_workitem_id 2
		.amdhsa_next_free_vgpr 256
		.amdhsa_next_free_sgpr 102
		.amdhsa_accum_offset 256
		.amdhsa_reserve_vcc 1
		.amdhsa_float_round_mode_32 0
		.amdhsa_float_round_mode_16_64 0
		.amdhsa_float_denorm_mode_32 3
		.amdhsa_float_denorm_mode_16_64 3
		.amdhsa_dx10_clamp 1
		.amdhsa_ieee_mode 1
		.amdhsa_fp16_overflow 0
		.amdhsa_tg_split 0
		.amdhsa_exception_fp_ieee_invalid_op 0
		.amdhsa_exception_fp_denorm_src 0
		.amdhsa_exception_fp_ieee_div_zero 0
		.amdhsa_exception_fp_ieee_overflow 0
		.amdhsa_exception_fp_ieee_underflow 0
		.amdhsa_exception_fp_ieee_inexact 0
		.amdhsa_exception_int_div_zero 0
	.end_amdhsa_kernel

amdhsa.kernels:
  - .agpr_count:     0
    .args:
      - .offset:         0
        .size:           168
        .value_kind:     by_value
      - .offset:         168
        .size:           4
        .value_kind:     hidden_block_count_x
      - .offset:         172
        .size:           4
        .value_kind:     hidden_block_count_y
      - .offset:         176
        .size:           4
        .value_kind:     hidden_block_count_z
      - .offset:         180
        .size:           2
        .value_kind:     hidden_group_size_x
      - .offset:         182
        .size:           2
        .value_kind:     hidden_group_size_y
      - .offset:         184
        .size:           2
        .value_kind:     hidden_group_size_z
      - .offset:         186
        .size:           2
        .value_kind:     hidden_remainder_x
      - .offset:         188
        .size:           2
        .value_kind:     hidden_remainder_y
      - .offset:         190
        .size:           2
        .value_kind:     hidden_remainder_z
      - .offset:         208
        .size:           8
        .value_kind:     hidden_global_offset_x
      - .offset:         216
        .size:           8
        .value_kind:     hidden_global_offset_y
      - .offset:         224
        .size:           8
        .value_kind:     hidden_global_offset_z
      - .offset:         232
        .size:           2
        .value_kind:     hidden_grid_dims
      - .offset:         256
        .size:           8
        .value_kind:     hidden_multigrid_sync_arg
      - .offset:         288
        .size:           4
        .value_kind:     hidden_dynamic_lds_size
    .group_segment_fixed_size: 0
    .kernarg_segment_align: 8
    .kernarg_segment_size: 424
    .language:       OpenCL C
    .language_version:
      - 2
      - 0
    .max_flat_workgroup_size: 512
    .name:           _Z8fwd_mega6Params
    .private_segment_fixed_size: 0
    .sgpr_count:     108
    .sgpr_spill_count: 105
    .symbol:         _Z8fwd_mega6Params.kd
    .uniform_work_group_size: 1
    .uses_dynamic_stack: false
    .vgpr_count:     256
    .vgpr_spill_count: 0
    .wavefront_size: 64
